# even in-proj GEMM: workgroups with 5 tiles (bx>=128) start 13us late so their epilogue HBM writes interleave with the others' main loops (uses their idle half round)
# baseline (speedup 1.0000x reference)
.LBB0_514:
	s_add_u32 s42, s22, 0xb100000
	s_addc_u32 s43, s23, 0
	s_add_u32 s56, s16, 0x300000
	s_addc_u32 s57, s17, 0
	s_add_u32 s6, s12, 0x4000000
	v_writelane_b32 v254, s6, 62
	s_addc_u32 s6, s13, 0
	v_writelane_b32 v255, s6, 0
	s_add_u32 s6, s14, 0x8000000
	s_addc_u32 s71, s15, 0
	s_add_u32 s68, s20, 0x1bb00000
	v_readlane_b32 s12, v254, 60
	s_addc_u32 s69, s21, 0
	s_mul_i32 s7, s12, 0x31800
	v_writelane_b32 v255, s6, 1
	s_mul_hi_u32 s6, s12, 0x31800
	s_add_u32 s4, s4, s7
	s_addc_u32 s5, s5, s6
	v_bfe_u32 v189, v15, 4, 2
	s_add_u32 s74, s4, 0x1b900000
	v_and_b32_e32 v1, 15, v15
	v_lshlrev_b32_e32 v17, 4, v189
	v_lshlrev_b32_e32 v15, 2, v15
	s_addc_u32 s75, s5, 0
	s_and_b32 s6, s38, 3
	v_lshl_or_b32 v17, v1, 6, v17
	s_lshl_b32 s4, s19, 13
	v_and_b32_e32 v15, 32, v15
	s_add_i32 m0, s59, 0x18000
	v_lshl_add_u64 v[8:9], v[8:9], 0, s[72:73]
	s_lshl_b32 s38, s19, 6
	v_bitop3_b32 v18, v17, s4, v15 bitop3:0xde
	s_lshl_b32 s39, s6, 5
	s_lshl_b32 s4, s6, 12
	s_waitcnt vmcnt(2)
	s_barrier
	global_load_lds_dwordx4 v[8:9], off
	v_lshl_add_u64 v[6:7], v[6:7], 0, s[72:73]
	s_add_i32 m0, s59, 0x1a000
	s_add_i32 s66, s59, 0x8000
	s_add_i32 s67, s59, 0xa000
	v_bitop3_b32 v242, v17, s4, v15 bitop3:0xde
	global_load_lds_dwordx4 v[6:7], off
	v_lshl_add_u64 v[2:3], v[2:3], 0, s[72:73]
	s_mov_b32 m0, s66
	s_add_u32 s4, s10, 0x40080
	global_load_lds_dwordx4 v[2:3], off
	v_lshl_add_u64 v[2:3], v[4:5], 0, s[72:73]
	s_mov_b32 m0, s67
	s_addc_u32 s5, s11, 0
	global_load_lds_dwordx4 v[2:3], off
	s_add_i32 m0, s59, 0x1c000
	v_lshl_add_u64 v[2:3], s[4:5], 0, v[174:175]
	global_load_lds_dwordx4 v[2:3], off
	v_lshl_add_u64 v[2:3], s[4:5], 0, v[170:171]
	s_add_i32 m0, s59, 0x1e000
	s_cmpk_lt_u32 s18, 0x100
	global_load_lds_dwordx4 v[2:3], off
	v_lshlrev_b32_e32 v2, 14, v14
	v_and_b32_e32 v2, 0xffff8000, v2
	v_lshl_add_u32 v2, v13, 11, v2
	v_and_b32_e32 v3, 1, v14
	v_lshl_or_b32 v2, v3, 6, v2
	v_lshl_add_u32 v190, v16, 1, v2
	v_lshlrev_b32_e32 v2, 14, v10
	v_and_b32_e32 v2, 0xffff8000, v2
	s_waitcnt vmcnt(6)
	s_cselect_b64 s[40:41], -1, 0
	s_bitcmp0_b32 s18, 6
	v_lshl_add_u32 v2, v11, 11, v2
	v_and_b32_e32 v3, 1, v10
	s_cselect_b64 s[4:5], -1, 0
	s_cmp_eq_u32 s6, 0
	v_lshl_or_b32 v2, v3, 6, v2
	v_readlane_b32 s6, v254, 45
	s_mov_b32 s70, 0
	s_cselect_b64 s[50:51], -1, 0
	v_mov_b32_e32 v191, v0
	v_lshl_add_u32 v192, v12, 1, v2
	v_mov_b32_e32 v193, v0
	v_add_u32_e32 v243, 0, v18
	v_readlane_b32 s18, v254, 24
	s_mov_b32 s14, s6
	v_readlane_b32 s13, v254, 61
	s_barrier
	v_readlane_b32 s7, v254, 46
	v_readlane_b32 s12, v254, 3
	s_cmpk_lt_u32 s12, 0x80
	s_cbranch_scc1 .Ldesync_skip_ine
	s_memrealtime vcc
	s_waitcnt lgkmcnt(0)
	s_add_u32 s12, vcc_lo, 0x514
.Ldesync_spin_ine:
	s_sleep 4
	s_memrealtime vcc
	s_waitcnt lgkmcnt(0)
	s_sub_u32 vcc_lo, vcc_lo, s12
	s_cmp_lt_i32 vcc_lo, 0
	s_cbranch_scc1 .Ldesync_spin_ine
.Ldesync_skip_ine:
	s_branch .LBB0_517
.LBB0_515:
	s_mov_b64 s[6:7], 0
